# topk: the pass header touches the four Q row blocks (both lists, both token tiles) so the later Q fragment loads hit in cache; on top of v058
# baseline (speedup 1.0000x reference)
.LBB0_20:
	v_mov_b32_e32 v119, v0
	s_barrier
	v_writelane_b32 v254, s16, 34
	v_readfirstlane_b32 s0, v119
	s_ashr_i32 s0, s0, 6
	s_lshl_b32 s38, s0, 1
	v_readlane_b32 s1, v254, 60
	v_bfe_u32 v6, v119, 5, 1
	s_add_i32 s40, s38, s1
	v_readlane_b32 s10, v254, 62
	s_lshl_b32 s1, s0, 12
	s_lshl_b32 s0, s0, 4
	s_lshl_b32 s42, s16, 6
	v_lshlrev_b32_e32 v2, 4, v6
	v_mov_b32_e32 v3, v155
	v_readlane_b32 s11, v254, 63
	s_add_i32 s43, s57, s1
	s_ashr_i32 s1, s0, 31
	s_ashr_i32 s20, s42, 31
	v_lshl_add_u64 v[4:5], s[10:11], 0, v[2:3]
	s_lshl_b64 s[10:11], s[0:1], 2
	s_add_u32 s0, s24, s10
	s_addc_u32 s1, s25, s11
	s_add_u32 s14, s26, s10
	s_addc_u32 s15, s27, s11
	s_or_b32 s18, s38, 1
	s_ashr_i32 s19, s18, 31
	s_ashr_i32 s39, s38, 31
	s_lshl_b64 s[18:19], s[18:19], 21
	v_and_b32_e32 v1, 31, v119
	s_lshl_b64 s[16:17], s[38:39], 21
	v_lshl_add_u64 v[64:65], v[4:5], 0, s[18:19]
	v_readlane_b32 s18, v255, 0
	v_lshlrev_b32_e32 v154, 7, v1
	v_lshl_add_u64 v[62:63], v[4:5], 0, s[16:17]
	s_or_b32 s16, s40, 1
	v_readlane_b32 s19, v255, 1
	s_ashr_i32 s41, s40, 31
	s_ashr_i32 s17, s16, 31
	v_lshl_add_u64 v[4:5], s[18:19], 0, v[154:155]
	v_cmp_lt_i32_e32 vcc, v215, v216
	s_lshl_b64 s[10:11], s[40:41], 14
	s_lshl_b64 s[16:17], s[16:17], 14
	v_lshl_add_u64 v[2:3], v[4:5], 0, v[2:3]
	v_lshlrev_b32_e32 v120, 2, v6
	v_cndmask_b32_e32 v7, v214, v215, vcc
	v_lshl_add_u64 v[66:67], v[2:3], 0, s[10:11]
	s_mov_b64 s[10:11], 0x1060
	s_mov_b64 s[18:19], 0x1000
	s_mov_b64 s[30:31], 0x1040
	s_mov_b64 s[34:35], 0x1020
	s_mov_b64 s[36:37], 0x2060
	s_mov_b64 s[38:39], 0x2000
	s_mov_b64 s[40:41], 0x2040
	s_mov_b64 s[44:45], 0x2020
	s_mov_b64 s[46:47], 0x3060
	s_mov_b64 s[48:49], 0x3000
	s_mov_b64 s[50:51], 0x3040
	s_mov_b64 s[52:53], 0x3020
	v_lshl_add_u64 v[90:91], v[2:3], 0, s[16:17]
	v_or_b32_e32 v232, s42, v1
	v_lshlrev_b32_e32 v232, 7, v232
	v_mov_b32_e32 v233, v155
	v_lshl_add_u64 v[234:235], v[62:63], 0, v[232:233]
	global_load_dwordx4 v[244:247], v[234:235], off
	v_lshl_add_u64 v[234:235], v[234:235], 0, s[18:19]
	global_load_dwordx4 v[244:247], v[234:235], off
	v_lshl_add_u64 v[234:235], v[64:65], 0, v[232:233]
	global_load_dwordx4 v[244:247], v[234:235], off
	v_lshl_add_u64 v[234:235], v[234:235], 0, s[18:19]
	global_load_dwordx4 v[244:247], v[234:235], off
	v_lshlrev_b32_e32 v121, 2, v7
	v_cmp_eq_u32_e64 s[12:13], 0, v6
	v_or_b32_e32 v122, 1, v120
	v_or_b32_e32 v123, 2, v120
	v_or_b32_e32 v124, 3, v120
	v_or_b32_e32 v125, 8, v120
	v_or_b32_e32 v126, 9, v120
	v_or_b32_e32 v127, 10, v120
	v_or_b32_e32 v128, 11, v120
	v_or_b32_e32 v129, 16, v120
	v_or_b32_e32 v136, 17, v120
	v_or_b32_e32 v137, 18, v120
	v_or_b32_e32 v138, 19, v120
	v_or_b32_e32 v139, 24, v120
	v_or_b32_e32 v140, 25, v120
	v_or_b32_e32 v141, 26, v120
	v_or_b32_e32 v142, 27, v120
	v_or_b32_e32 v143, 32, v120
	v_or_b32_e32 v144, 33, v120
	v_or_b32_e32 v145, 34, v120
	v_or_b32_e32 v146, 35, v120
	v_or_b32_e32 v147, 40, v120
	v_or_b32_e32 v148, 41, v120
	v_or_b32_e32 v149, 42, v120
	v_or_b32_e32 v150, 43, v120
	v_or_b32_e32 v151, 48, v120
	v_or_b32_e32 v152, 49, v120
	v_or_b32_e32 v153, 50, v120
	v_or_b32_e32 v160, 51, v120
	v_or_b32_e32 v161, 56, v120
	v_or_b32_e32 v162, 57, v120
	v_or_b32_e32 v163, 58, v120
	v_or_b32_e32 v164, 59, v120
	v_or_b32_e32 v165, 64, v120
	v_or_b32_e32 v166, 0x41, v120
	v_or_b32_e32 v167, 0x42, v120
	v_or_b32_e32 v168, 0x43, v120
	v_or_b32_e32 v169, 0x48, v120
	v_or_b32_e32 v170, 0x49, v120
	v_or_b32_e32 v171, 0x4a, v120
	v_or_b32_e32 v172, 0x4b, v120
	v_or_b32_e32 v173, 0x50, v120
	v_or_b32_e32 v174, 0x51, v120
	v_or_b32_e32 v175, 0x52, v120
	v_or_b32_e32 v184, 0x53, v120
	v_or_b32_e32 v185, 0x58, v120
	v_or_b32_e32 v186, 0x59, v120
	v_or_b32_e32 v187, 0x5a, v120
	v_or_b32_e32 v188, 0x5b, v120
	v_or_b32_e32 v189, 0x60, v120
	v_or_b32_e32 v190, 0x61, v120
	v_or_b32_e32 v191, 0x62, v120
	v_or_b32_e32 v192, 0x63, v120
	v_or_b32_e32 v193, 0x68, v120
	v_or_b32_e32 v194, 0x69, v120
	v_or_b32_e32 v195, 0x6a, v120
	v_or_b32_e32 v196, 0x6b, v120
	v_or_b32_e32 v197, 0x70, v120
	v_or_b32_e32 v198, 0x71, v120
	v_or_b32_e32 v199, 0x72, v120
	v_or_b32_e32 v200, 0x73, v120
	v_or_b32_e32 v201, 0x78, v120
	v_or_b32_e32 v202, 0x79, v120
	v_or_b32_e32 v203, 0x7a, v120
	v_or_b32_e32 v204, 0x7b, v120
	v_lshl_add_u64 v[68:69], v[66:67], 0, s[18:19]
	v_lshl_add_u64 v[70:71], v[66:67], 0, s[38:39]
	v_lshl_add_u64 v[72:73], v[66:67], 0, s[48:49]
	v_lshl_add_u64 v[92:93], v[90:91], 0, s[18:19]
	v_lshl_add_u64 v[94:95], v[90:91], 0, s[38:39]
	v_lshl_add_u64 v[96:97], v[90:91], 0, s[48:49]
	v_or_b32_e32 v118, s42, v1
	v_mov_b32_e32 v1, s20
	s_mov_b64 s[38:39], -1
	s_mov_b32 s44, 0
	s_branch .LBB0_22
